# slot participation derived from gridDim (1152 mod G) instead of hard-coded 128/1024; otherwise as previous P0 off-load version
# speedup vs baseline: 1.0052x; 1.0052x over previous
; #define PHASE_IDS() int lane = lane_id_fresh(); int wave = wave_s; asm volatile("" : "+s"(wave)); \
;         int bid = blockIdx.x; asm volatile("" : "+s"(bid)); int G = gridDim.x; asm volatile("" : "+s"(G)); \
;         const int tid = wave * 64 + lane, gw = bid * NWAVES + wave, NGW = G * NWAVES; (void)tid; (void)gw; (void)NGW
; DI void phase_p0(const Params& p, LAS unsigned char* lds, int gw, int NGW, int wave, int lane) {
;     ...
;     for (int it = gw; it < NITEMS; it += NGW) {
;         int r = it;
;         if (r < 2 * I_INA) { const int j = r / I_INA; p0_transpose_item(p.w_in_a + (size_t)j * D * NA, D, NA, (bf16_t*)(p.ws + WS_W + j * WPAIR + WO_INA), scr, r % I_INA, lane); continue; } r -= 2 * I_INA;
;         if (r < 2 * I_OUT) { const int j = r / I_OUT; p0_transpose_item(p.w_out_a + (size_t)j * D * D, D, D, (bf16_t*)(p.ws + WS_W + j * WPAIR + WO_OUTA), scr, r % I_OUT, lane); continue; } r -= 2 * I_OUT;
;         if (r < 2 * I_INB) { const int j = r / I_INB; p0_transpose_item(p.w_in_b + (size_t)j * D * NB, D, NB, (bf16_t*)(p.ws + WS_W + j * WPAIR + WO_INB), scr, r % I_INB, lane); continue; } r -= 2 * I_INB;
;         { const int j = r / I_OUT; p0_transpose_item(p.w_out_b + (size_t)j * D * D, D, D, (bf16_t*)(p.ws + WS_W + j * WPAIR + WO_OUTB), scr, r % I_OUT, lane); }
;     }
; __global__ void __launch_bounds__(NTHREADS) hybrid_fwd(Params p) {
;     ...
;             PHASE_IDS();
;             const int N = isA ? NA : NB;
;             const bf16_t* wt = isA ? (const bf16_t*)(p.ws + WS_W + j * WPAIR + WO_INA) : (const bf16_t*)(p.ws + WS_W + j * WPAIR + WO_INB);
;             pg8::StaticOrder S; S.init(SEQ, N, G, bid);
;             pg8::Gemm g{hb, wt, SEQ, N, D, D, 0};
;             pg8::EpiBf16 E{z, 0, N / 256}; pg8::gemm_phase<pg8::EpiBf16>(lds, g, S, E, tid);
;             meta_gemm<false>(hb + (size_t)SEQ * D, D, wt, N, z, 0, N / 256, lds, bid, G, wave, lane);
.LBB0_74:
	s_bitcmp1_b32 s20, 0
	s_cbranch_scc1 .Lslot_skip
	s_movk_i32 s5, 0x480
.Lslot_mod:
	s_cmp_lt_u32 s5, s99
	s_cbranch_scc1 .Lslot_mod_done
	s_sub_u32 s5, s5, s99
	s_branch .Lslot_mod
.Lslot_mod_done:
	v_readlane_b32 s4, v239, 0
	s_cmp_lt_u32 s4, s5
	s_cbranch_scc1 .Lslot_skip
	s_waitcnt vmcnt(0) lgkmcnt(0)
	s_barrier
	v_writelane_b32 v246, s0, 0
	v_writelane_b32 v246, s1, 1
	v_writelane_b32 v246, s2, 2
	v_writelane_b32 v246, s3, 3
	v_writelane_b32 v246, s4, 4
	v_writelane_b32 v246, s5, 5
	v_writelane_b32 v246, s6, 6
	v_writelane_b32 v246, s7, 7
	v_writelane_b32 v246, s8, 8
	v_writelane_b32 v246, s9, 9
	v_writelane_b32 v246, s10, 10
	v_writelane_b32 v246, s11, 11
	v_writelane_b32 v246, s12, 12
	v_writelane_b32 v246, s13, 13
	v_writelane_b32 v246, s14, 14
	v_writelane_b32 v246, s15, 15
	v_writelane_b32 v246, s16, 16
	v_writelane_b32 v246, s17, 17
	v_writelane_b32 v246, s18, 18
	v_writelane_b32 v246, s19, 19
	v_writelane_b32 v246, s20, 20
	v_writelane_b32 v246, s21, 21
	v_writelane_b32 v246, s22, 22
	v_writelane_b32 v246, s23, 23
	v_writelane_b32 v246, s24, 24
	v_writelane_b32 v246, s25, 25
	v_writelane_b32 v246, s26, 26
	v_writelane_b32 v246, s27, 27
	v_writelane_b32 v246, s28, 28
	v_writelane_b32 v246, s29, 29
	v_writelane_b32 v246, s30, 30
	v_writelane_b32 v246, s31, 31
	v_writelane_b32 v246, s32, 32
	v_writelane_b32 v246, s33, 33
	v_writelane_b32 v246, s34, 34
	v_writelane_b32 v246, s35, 35
	v_writelane_b32 v246, s36, 36
	v_writelane_b32 v246, s37, 37
	v_writelane_b32 v246, s38, 38
	v_writelane_b32 v246, s39, 39
	v_writelane_b32 v246, s40, 40
	v_writelane_b32 v246, s41, 41
	v_writelane_b32 v246, s42, 42
	v_writelane_b32 v246, s43, 43
	v_writelane_b32 v246, s44, 44
	v_writelane_b32 v246, s45, 45
	v_writelane_b32 v246, s46, 46
	v_writelane_b32 v246, s47, 47
	v_writelane_b32 v246, s48, 48
	v_writelane_b32 v246, s49, 49
	v_writelane_b32 v246, s50, 50
	v_writelane_b32 v246, s51, 51
	v_writelane_b32 v246, s52, 52
	v_writelane_b32 v246, s53, 53
	v_writelane_b32 v246, s54, 54
	v_writelane_b32 v246, s55, 55
	v_writelane_b32 v246, s56, 56
	v_writelane_b32 v246, s57, 57
	v_writelane_b32 v246, s58, 58
	v_writelane_b32 v246, s59, 59
	v_writelane_b32 v246, s60, 60
	v_writelane_b32 v246, s61, 61
	v_writelane_b32 v246, s62, 62
	v_writelane_b32 v246, s63, 63
	v_writelane_b32 v247, s64, 0
	v_writelane_b32 v247, s65, 1
	v_writelane_b32 v247, s66, 2
	v_writelane_b32 v247, s67, 3
	v_writelane_b32 v247, s68, 4
	v_writelane_b32 v247, s69, 5
	v_writelane_b32 v247, s70, 6
	v_writelane_b32 v247, s71, 7
	v_writelane_b32 v247, s72, 8
	v_writelane_b32 v247, s73, 9
	v_writelane_b32 v247, s74, 10
	v_writelane_b32 v247, s75, 11
	v_writelane_b32 v247, s76, 12
	v_writelane_b32 v247, s77, 13
	v_writelane_b32 v247, s78, 14
	v_writelane_b32 v247, s79, 15
	v_writelane_b32 v247, s80, 16
	v_writelane_b32 v247, s81, 17
	v_writelane_b32 v247, s82, 18
	v_writelane_b32 v247, s83, 19
	v_writelane_b32 v247, s84, 20
	v_writelane_b32 v247, s85, 21
	v_writelane_b32 v247, s86, 22
	v_writelane_b32 v247, s87, 23
	v_writelane_b32 v247, s88, 24
	v_writelane_b32 v247, s89, 25
	v_writelane_b32 v247, s90, 26
	v_writelane_b32 v247, s91, 27
	v_writelane_b32 v247, s92, 28
	v_writelane_b32 v247, s93, 29
	v_writelane_b32 v247, s94, 30
	v_writelane_b32 v247, s95, 31
	v_writelane_b32 v247, s96, 32
	v_writelane_b32 v247, s97, 33
	v_writelane_b32 v247, s98, 34
	v_writelane_b32 v247, s99, 35
	v_writelane_b32 v247, vcc_lo, 36
	v_writelane_b32 v247, vcc_hi, 37
	v_readlane_b32 s89, v239, 0
	v_readlane_b32 s91, v239, 1
	v_readlane_b32 s92, v245, 0
	v_readlane_b32 s93, v245, 1
	s_lshr_b32 s90, s20, 1
	s_sub_i32 s89, s89, s5
	s_lshl_b32 s89, s89, 3
	s_add_i32 s89, s89, s91
	s_nop 4
	s_load_dwordx16 s[72:87], s[92:93], 0x0
	s_mov_b32 s88, 0
	s_waitcnt lgkmcnt(0)
	s_sub_i32 s92, s99, s5
	s_lshl_b32 s92, s92, 3

; DI void phase_p0(const Params& p, LAS unsigned char* lds, int gw, int NGW, int wave, int lane) {
;     ...
;     for (int it = gw; it < NITEMS; it += NGW) {
;         int r = it;
;         if (r < 2 * I_INA) { const int j = r / I_INA; p0_transpose_item(p.w_in_a + (size_t)j * D * NA, D, NA, (bf16_t*)(p.ws + WS_W + j * WPAIR + WO_INA), scr, r % I_INA, lane); continue; } r -= 2 * I_INA;
;         if (r < 2 * I_OUT) { const int j = r / I_OUT; p0_transpose_item(p.w_out_a + (size_t)j * D * D, D, D, (bf16_t*)(p.ws + WS_W + j * WPAIR + WO_OUTA), scr, r % I_OUT, lane); continue; } r -= 2 * I_OUT;
;         if (r < 2 * I_INB) { const int j = r / I_INB; p0_transpose_item(p.w_in_b + (size_t)j * D * NB, D, NB, (bf16_t*)(p.ws + WS_W + j * WPAIR + WO_INB), scr, r % I_INB, lane); continue; } r -= 2 * I_INB;
;         { const int j = r / I_OUT; p0_transpose_item(p.w_out_b + (size_t)j * D * D, D, D, (bf16_t*)(p.ws + WS_W + j * WPAIR + WO_OUTB), scr, r % I_OUT, lane); }
;     }
.Lslot_go:
	s_add_i32 s88, s88, 1
	s_add_i32 s4, s4, s89
	s_mov_b32 s0, s92
	s_mov_b32 s1, s91
	v_mbcnt_lo_u32_b32 v1, -1, 0
	v_mbcnt_hi_u32_b32 v1, -1, v1
	v_lshl_add_u32 v34, s91, 6, v1
	s_branch .Lp0_pre
